# FFN-up EpiSwiglu epilogue rewritten with packed fp32 ops (v_pk_mul/add_f32) and batched transcendentals: 527 -> 323 instructions, same operation order
# speedup vs baseline: 1.0017x; 1.0017x over previous
.LBB0_1578:
	s_andn2_b64 vcc, exec, s[4:5]
	s_mov_b64 s[60:61], 0x9400300
	v_lshl_or_b32 v144, s25, 7, v148
	v_lshl_add_u32 v150, s24, 8, v146
	v_ashrrev_i32_e32 v145, 31, v144
	v_mov_b64_e32 v[142:143], s[12:13]
	s_movk_i32 s17, 0x1600
	v_mad_i64_i32 v[152:153], s[24:25], v150, s17, v[142:143]
	v_lshlrev_b64 v[144:145], 1, v[144:145]
	v_lshl_add_u64 v[152:153], v[152:153], 0, v[144:145]
	s_mov_b32 s98, 0xbfb8aa3b
	s_mov_b32 s100, 1.0
	v_pk_mul_f32 v[160:161], v[128:129], s[98:99] op_sel_hi:[1,0]
	v_pk_mul_f32 v[162:163], v[130:131], s[98:99] op_sel_hi:[1,0]
	v_pk_mul_f32 v[164:165], v[120:121], s[98:99] op_sel_hi:[1,0]
	v_pk_mul_f32 v[166:167], v[122:123], s[98:99] op_sel_hi:[1,0]
	v_exp_f32_e32 v160, v160
	v_exp_f32_e32 v161, v161
	v_exp_f32_e32 v162, v162
	v_exp_f32_e32 v163, v163
	v_exp_f32_e32 v164, v164
	v_exp_f32_e32 v165, v165
	v_exp_f32_e32 v166, v166
	v_exp_f32_e32 v167, v167
	v_pk_add_f32 v[160:161], v[160:161], s[100:101] op_sel_hi:[1,0]
	v_pk_add_f32 v[162:163], v[162:163], s[100:101] op_sel_hi:[1,0]
	v_pk_add_f32 v[164:165], v[164:165], s[100:101] op_sel_hi:[1,0]
	v_pk_add_f32 v[166:167], v[166:167], s[100:101] op_sel_hi:[1,0]
	v_rcp_f32_e32 v160, v160
	v_rcp_f32_e32 v161, v161
	v_rcp_f32_e32 v162, v162
	v_rcp_f32_e32 v163, v163
	v_rcp_f32_e32 v164, v164
	v_rcp_f32_e32 v165, v165
	v_rcp_f32_e32 v166, v166
	v_rcp_f32_e32 v167, v167
	v_pk_mul_f32 v[160:161], v[128:129], v[160:161]
	v_pk_mul_f32 v[162:163], v[130:131], v[162:163]
	v_pk_mul_f32 v[164:165], v[120:121], v[164:165]
	v_pk_mul_f32 v[166:167], v[122:123], v[166:167]
	v_pk_mul_f32 v[160:161], v[160:161], v[124:125]
	v_pk_mul_f32 v[162:163], v[162:163], v[126:127]
	v_pk_mul_f32 v[164:165], v[164:165], v[116:117]
	v_pk_mul_f32 v[166:167], v[166:167], v[118:119]
	v_cvt_pk_bf16_f32 v176, v160, v161
	v_cvt_pk_bf16_f32 v177, v162, v163
	v_cvt_pk_bf16_f32 v178, v164, v165
	v_cvt_pk_bf16_f32 v179, v166, v167
	global_store_dwordx4 v[152:153], v[176:179], off
	v_pk_mul_f32 v[160:161], v[112:113], s[98:99] op_sel_hi:[1,0]
	v_pk_mul_f32 v[162:163], v[114:115], s[98:99] op_sel_hi:[1,0]
	v_pk_mul_f32 v[164:165], v[104:105], s[98:99] op_sel_hi:[1,0]
	v_pk_mul_f32 v[166:167], v[106:107], s[98:99] op_sel_hi:[1,0]
	s_mov_b64 s[24:25], 0x16000
	v_exp_f32_e32 v160, v160
	v_exp_f32_e32 v161, v161
	v_exp_f32_e32 v162, v162
	v_exp_f32_e32 v163, v163
	v_exp_f32_e32 v164, v164
	v_exp_f32_e32 v165, v165
	v_exp_f32_e32 v166, v166
	v_exp_f32_e32 v167, v167
	v_lshl_add_u64 v[186:187], v[152:153], 0, s[24:25]
	v_pk_add_f32 v[160:161], v[160:161], s[100:101] op_sel_hi:[1,0]
	v_pk_add_f32 v[162:163], v[162:163], s[100:101] op_sel_hi:[1,0]
	v_pk_add_f32 v[164:165], v[164:165], s[100:101] op_sel_hi:[1,0]
	v_pk_add_f32 v[166:167], v[166:167], s[100:101] op_sel_hi:[1,0]
	v_rcp_f32_e32 v160, v160
	v_rcp_f32_e32 v161, v161
	v_rcp_f32_e32 v162, v162
	v_rcp_f32_e32 v163, v163
	v_rcp_f32_e32 v164, v164
	v_rcp_f32_e32 v165, v165
	v_rcp_f32_e32 v166, v166
	v_rcp_f32_e32 v167, v167
	v_pk_mul_f32 v[160:161], v[112:113], v[160:161]
	v_pk_mul_f32 v[162:163], v[114:115], v[162:163]
	v_pk_mul_f32 v[164:165], v[104:105], v[164:165]
	v_pk_mul_f32 v[166:167], v[106:107], v[166:167]
	v_pk_mul_f32 v[160:161], v[160:161], v[108:109]
	v_pk_mul_f32 v[162:163], v[162:163], v[110:111]
	v_pk_mul_f32 v[164:165], v[164:165], v[100:101]
	v_pk_mul_f32 v[166:167], v[166:167], v[102:103]
	v_cvt_pk_bf16_f32 v180, v160, v161
	v_cvt_pk_bf16_f32 v181, v162, v163
	v_cvt_pk_bf16_f32 v182, v164, v165
	v_cvt_pk_bf16_f32 v183, v166, v167
	global_store_dwordx4 v[186:187], v[180:183], off
	v_pk_mul_f32 v[160:161], v[96:97], s[98:99] op_sel_hi:[1,0]
	v_pk_mul_f32 v[162:163], v[98:99], s[98:99] op_sel_hi:[1,0]
	v_pk_mul_f32 v[164:165], v[88:89], s[98:99] op_sel_hi:[1,0]
	v_pk_mul_f32 v[166:167], v[90:91], s[98:99] op_sel_hi:[1,0]
	s_mov_b64 s[24:25], 0x2c000
	v_exp_f32_e32 v160, v160
	v_exp_f32_e32 v161, v161
	v_exp_f32_e32 v162, v162
	v_exp_f32_e32 v163, v163
	v_exp_f32_e32 v164, v164
	v_exp_f32_e32 v165, v165
	v_exp_f32_e32 v166, v166
	v_exp_f32_e32 v167, v167
	v_lshl_add_u64 v[184:185], v[152:153], 0, s[24:25]
	v_pk_add_f32 v[160:161], v[160:161], s[100:101] op_sel_hi:[1,0]
	v_pk_add_f32 v[162:163], v[162:163], s[100:101] op_sel_hi:[1,0]
	v_pk_add_f32 v[164:165], v[164:165], s[100:101] op_sel_hi:[1,0]
	v_pk_add_f32 v[166:167], v[166:167], s[100:101] op_sel_hi:[1,0]
	v_rcp_f32_e32 v160, v160
	v_rcp_f32_e32 v161, v161
	v_rcp_f32_e32 v162, v162
	v_rcp_f32_e32 v163, v163
	v_rcp_f32_e32 v164, v164
	v_rcp_f32_e32 v165, v165
	v_rcp_f32_e32 v166, v166
	v_rcp_f32_e32 v167, v167
	v_pk_mul_f32 v[160:161], v[96:97], v[160:161]
	v_pk_mul_f32 v[162:163], v[98:99], v[162:163]
	v_pk_mul_f32 v[164:165], v[88:89], v[164:165]
	v_pk_mul_f32 v[166:167], v[90:91], v[166:167]
	v_pk_mul_f32 v[160:161], v[160:161], v[92:93]
	v_pk_mul_f32 v[162:163], v[162:163], v[94:95]
	v_pk_mul_f32 v[164:165], v[164:165], v[84:85]
	v_pk_mul_f32 v[166:167], v[166:167], v[86:87]
	v_cvt_pk_bf16_f32 v176, v160, v161
	v_cvt_pk_bf16_f32 v177, v162, v163
	v_cvt_pk_bf16_f32 v178, v164, v165
	v_cvt_pk_bf16_f32 v179, v166, v167
	global_store_dwordx4 v[184:185], v[176:179], off
	v_pk_mul_f32 v[160:161], v[80:81], s[98:99] op_sel_hi:[1,0]
	v_pk_mul_f32 v[162:163], v[82:83], s[98:99] op_sel_hi:[1,0]
	v_pk_mul_f32 v[164:165], v[72:73], s[98:99] op_sel_hi:[1,0]
	v_pk_mul_f32 v[166:167], v[74:75], s[98:99] op_sel_hi:[1,0]
	s_mov_b64 s[24:25], 0x42000
	v_exp_f32_e32 v160, v160
	v_exp_f32_e32 v161, v161
	v_exp_f32_e32 v162, v162
	v_exp_f32_e32 v163, v163
	v_exp_f32_e32 v164, v164
	v_exp_f32_e32 v165, v165
	v_exp_f32_e32 v166, v166
	v_exp_f32_e32 v167, v167
	v_lshl_add_u64 v[186:187], v[152:153], 0, s[24:25]
	v_pk_add_f32 v[160:161], v[160:161], s[100:101] op_sel_hi:[1,0]
	v_pk_add_f32 v[162:163], v[162:163], s[100:101] op_sel_hi:[1,0]
	v_pk_add_f32 v[164:165], v[164:165], s[100:101] op_sel_hi:[1,0]
	v_pk_add_f32 v[166:167], v[166:167], s[100:101] op_sel_hi:[1,0]
	v_rcp_f32_e32 v160, v160
	v_rcp_f32_e32 v161, v161
	v_rcp_f32_e32 v162, v162
	v_rcp_f32_e32 v163, v163
	v_rcp_f32_e32 v164, v164
	v_rcp_f32_e32 v165, v165
	v_rcp_f32_e32 v166, v166
	v_rcp_f32_e32 v167, v167
	v_pk_mul_f32 v[160:161], v[80:81], v[160:161]
	v_pk_mul_f32 v[162:163], v[82:83], v[162:163]
	v_pk_mul_f32 v[164:165], v[72:73], v[164:165]
	v_pk_mul_f32 v[166:167], v[74:75], v[166:167]
	v_pk_mul_f32 v[160:161], v[160:161], v[76:77]
	v_pk_mul_f32 v[162:163], v[162:163], v[78:79]
	v_pk_mul_f32 v[164:165], v[164:165], v[68:69]
	v_pk_mul_f32 v[166:167], v[166:167], v[70:71]
	v_cvt_pk_bf16_f32 v180, v160, v161
	v_cvt_pk_bf16_f32 v181, v162, v163
	v_cvt_pk_bf16_f32 v182, v164, v165
	v_cvt_pk_bf16_f32 v183, v166, v167
	global_store_dwordx4 v[186:187], v[180:183], off
	v_pk_mul_f32 v[160:161], v[64:65], s[98:99] op_sel_hi:[1,0]
	v_pk_mul_f32 v[162:163], v[66:67], s[98:99] op_sel_hi:[1,0]
	v_pk_mul_f32 v[164:165], v[56:57], s[98:99] op_sel_hi:[1,0]
	v_pk_mul_f32 v[166:167], v[58:59], s[98:99] op_sel_hi:[1,0]
	s_mov_b64 s[24:25], 0xb0000
	v_exp_f32_e32 v160, v160
	v_exp_f32_e32 v161, v161
	v_exp_f32_e32 v162, v162
	v_exp_f32_e32 v163, v163
	v_exp_f32_e32 v164, v164
	v_exp_f32_e32 v165, v165
	v_exp_f32_e32 v166, v166
	v_exp_f32_e32 v167, v167
	v_lshl_add_u64 v[184:185], v[152:153], 0, s[24:25]
	v_pk_add_f32 v[160:161], v[160:161], s[100:101] op_sel_hi:[1,0]
	v_pk_add_f32 v[162:163], v[162:163], s[100:101] op_sel_hi:[1,0]
	v_pk_add_f32 v[164:165], v[164:165], s[100:101] op_sel_hi:[1,0]
	v_pk_add_f32 v[166:167], v[166:167], s[100:101] op_sel_hi:[1,0]
	v_rcp_f32_e32 v160, v160
	v_rcp_f32_e32 v161, v161
	v_rcp_f32_e32 v162, v162
	v_rcp_f32_e32 v163, v163
	v_rcp_f32_e32 v164, v164
	v_rcp_f32_e32 v165, v165
	v_rcp_f32_e32 v166, v166
	v_rcp_f32_e32 v167, v167
	v_pk_mul_f32 v[160:161], v[64:65], v[160:161]
	v_pk_mul_f32 v[162:163], v[66:67], v[162:163]
	v_pk_mul_f32 v[164:165], v[56:57], v[164:165]
	v_pk_mul_f32 v[166:167], v[58:59], v[166:167]
	v_pk_mul_f32 v[160:161], v[160:161], v[60:61]
	v_pk_mul_f32 v[162:163], v[162:163], v[62:63]
	v_pk_mul_f32 v[164:165], v[164:165], v[52:53]
	v_pk_mul_f32 v[166:167], v[166:167], v[54:55]
	v_cvt_pk_bf16_f32 v176, v160, v161
	v_cvt_pk_bf16_f32 v177, v162, v163
	v_cvt_pk_bf16_f32 v178, v164, v165
	v_cvt_pk_bf16_f32 v179, v166, v167
	global_store_dwordx4 v[184:185], v[176:179], off
	v_pk_mul_f32 v[160:161], v[48:49], s[98:99] op_sel_hi:[1,0]
	v_pk_mul_f32 v[162:163], v[50:51], s[98:99] op_sel_hi:[1,0]
	v_pk_mul_f32 v[164:165], v[40:41], s[98:99] op_sel_hi:[1,0]
	v_pk_mul_f32 v[166:167], v[42:43], s[98:99] op_sel_hi:[1,0]
	s_mov_b64 s[24:25], 0xc6000
	v_exp_f32_e32 v160, v160
	v_exp_f32_e32 v161, v161
	v_exp_f32_e32 v162, v162
	v_exp_f32_e32 v163, v163
	v_exp_f32_e32 v164, v164
	v_exp_f32_e32 v165, v165
	v_exp_f32_e32 v166, v166
	v_exp_f32_e32 v167, v167
	v_lshl_add_u64 v[186:187], v[152:153], 0, s[24:25]
	v_pk_add_f32 v[160:161], v[160:161], s[100:101] op_sel_hi:[1,0]
	v_pk_add_f32 v[162:163], v[162:163], s[100:101] op_sel_hi:[1,0]
	v_pk_add_f32 v[164:165], v[164:165], s[100:101] op_sel_hi:[1,0]
	v_pk_add_f32 v[166:167], v[166:167], s[100:101] op_sel_hi:[1,0]
	v_rcp_f32_e32 v160, v160
	v_rcp_f32_e32 v161, v161
	v_rcp_f32_e32 v162, v162
	v_rcp_f32_e32 v163, v163
	v_rcp_f32_e32 v164, v164
	v_rcp_f32_e32 v165, v165
	v_rcp_f32_e32 v166, v166
	v_rcp_f32_e32 v167, v167
	v_pk_mul_f32 v[160:161], v[48:49], v[160:161]
	v_pk_mul_f32 v[162:163], v[50:51], v[162:163]
	v_pk_mul_f32 v[164:165], v[40:41], v[164:165]
	v_pk_mul_f32 v[166:167], v[42:43], v[166:167]
	v_pk_mul_f32 v[160:161], v[160:161], v[44:45]
	v_pk_mul_f32 v[162:163], v[162:163], v[46:47]
	v_pk_mul_f32 v[164:165], v[164:165], v[36:37]
	v_pk_mul_f32 v[166:167], v[166:167], v[38:39]
	v_cvt_pk_bf16_f32 v180, v160, v161
	v_cvt_pk_bf16_f32 v181, v162, v163
	v_cvt_pk_bf16_f32 v182, v164, v165
	v_cvt_pk_bf16_f32 v183, v166, v167
	global_store_dwordx4 v[186:187], v[180:183], off
	v_pk_mul_f32 v[160:161], v[32:33], s[98:99] op_sel_hi:[1,0]
	v_pk_mul_f32 v[162:163], v[34:35], s[98:99] op_sel_hi:[1,0]
	v_pk_mul_f32 v[164:165], v[24:25], s[98:99] op_sel_hi:[1,0]
	v_pk_mul_f32 v[166:167], v[26:27], s[98:99] op_sel_hi:[1,0]
	s_mov_b64 s[24:25], 0xdc000
	v_exp_f32_e32 v160, v160
	v_exp_f32_e32 v161, v161
	v_exp_f32_e32 v162, v162
	v_exp_f32_e32 v163, v163
	v_exp_f32_e32 v164, v164
	v_exp_f32_e32 v165, v165
	v_exp_f32_e32 v166, v166
	v_exp_f32_e32 v167, v167
	v_lshl_add_u64 v[184:185], v[152:153], 0, s[24:25]
	v_pk_add_f32 v[160:161], v[160:161], s[100:101] op_sel_hi:[1,0]
	v_pk_add_f32 v[162:163], v[162:163], s[100:101] op_sel_hi:[1,0]
	v_pk_add_f32 v[164:165], v[164:165], s[100:101] op_sel_hi:[1,0]
	v_pk_add_f32 v[166:167], v[166:167], s[100:101] op_sel_hi:[1,0]
	v_rcp_f32_e32 v160, v160
	v_rcp_f32_e32 v161, v161
	v_rcp_f32_e32 v162, v162
	v_rcp_f32_e32 v163, v163
	v_rcp_f32_e32 v164, v164
	v_rcp_f32_e32 v165, v165
	v_rcp_f32_e32 v166, v166
	v_rcp_f32_e32 v167, v167
	v_pk_mul_f32 v[160:161], v[32:33], v[160:161]
	v_pk_mul_f32 v[162:163], v[34:35], v[162:163]
	v_pk_mul_f32 v[164:165], v[24:25], v[164:165]
	v_pk_mul_f32 v[166:167], v[26:27], v[166:167]
	v_pk_mul_f32 v[160:161], v[160:161], v[28:29]
	v_pk_mul_f32 v[162:163], v[162:163], v[30:31]
	v_pk_mul_f32 v[164:165], v[164:165], v[20:21]
	v_pk_mul_f32 v[166:167], v[166:167], v[22:23]
	v_cvt_pk_bf16_f32 v176, v160, v161
	v_cvt_pk_bf16_f32 v177, v162, v163
	v_cvt_pk_bf16_f32 v178, v164, v165
	v_cvt_pk_bf16_f32 v179, v166, v167
	global_store_dwordx4 v[184:185], v[176:179], off
	v_pk_mul_f32 v[160:161], v[16:17], s[98:99] op_sel_hi:[1,0]
	v_pk_mul_f32 v[162:163], v[18:19], s[98:99] op_sel_hi:[1,0]
	v_pk_mul_f32 v[164:165], v[8:9], s[98:99] op_sel_hi:[1,0]
	v_pk_mul_f32 v[166:167], v[10:11], s[98:99] op_sel_hi:[1,0]
	s_mov_b64 s[24:25], 0xf2000
	v_exp_f32_e32 v160, v160
	v_exp_f32_e32 v161, v161
	v_exp_f32_e32 v162, v162
	v_exp_f32_e32 v163, v163
	v_exp_f32_e32 v164, v164
	v_exp_f32_e32 v165, v165
	v_exp_f32_e32 v166, v166
	v_exp_f32_e32 v167, v167
	v_lshl_add_u64 v[186:187], v[152:153], 0, s[24:25]
	v_pk_add_f32 v[160:161], v[160:161], s[100:101] op_sel_hi:[1,0]
	v_pk_add_f32 v[162:163], v[162:163], s[100:101] op_sel_hi:[1,0]
	v_pk_add_f32 v[164:165], v[164:165], s[100:101] op_sel_hi:[1,0]
	v_pk_add_f32 v[166:167], v[166:167], s[100:101] op_sel_hi:[1,0]
	v_rcp_f32_e32 v160, v160
	v_rcp_f32_e32 v161, v161
	v_rcp_f32_e32 v162, v162
	v_rcp_f32_e32 v163, v163
	v_rcp_f32_e32 v164, v164
	v_rcp_f32_e32 v165, v165
	v_rcp_f32_e32 v166, v166
	v_rcp_f32_e32 v167, v167
	v_pk_mul_f32 v[160:161], v[16:17], v[160:161]
	v_pk_mul_f32 v[162:163], v[18:19], v[162:163]
	v_pk_mul_f32 v[164:165], v[8:9], v[164:165]
	v_pk_mul_f32 v[166:167], v[10:11], v[166:167]
	v_pk_mul_f32 v[160:161], v[160:161], v[12:13]
	v_pk_mul_f32 v[162:163], v[162:163], v[14:15]
	v_pk_mul_f32 v[164:165], v[164:165], v[4:5]
	v_pk_mul_f32 v[166:167], v[166:167], v[6:7]
	v_cvt_pk_bf16_f32 v180, v160, v161
	v_cvt_pk_bf16_f32 v181, v162, v163
	v_cvt_pk_bf16_f32 v182, v164, v165
	v_cvt_pk_bf16_f32 v183, v166, v167
	global_store_dwordx4 v[186:187], v[180:183], off
	s_mov_b64 s[24:25], -1
	s_cbranch_vccnz .LBB0_1567
	s_andn2_b64 vcc, exec, s[10:11]
	s_cbranch_vccnz .LBB0_1566
	s_barrier
	s_branch .LBB0_1566
